# inproj epilogue: fast paths also for the K|V tile and the kidx|w_i|qkv tile
# speedup vs baseline: 1.2247x; 1.0115x over previous
.LBB0_1001:
	s_or_b64 exec, exec, s[0:1]
	s_mov_b32 s53, 0
	s_cmp_lt_u32 s80, 2
	s_cbranch_scc1 .Lipf_hq
	s_sub_u32 s0, s80, 3
	s_cmp_lt_u32 s0, 2
	s_cbranch_scc1 .Lipf_hqi
	s_sub_u32 s0, s80, 6
	s_cmp_lt_u32 s0, 5
	s_cbranch_scc1 .Lipf_hqkv
	s_cmp_eq_u32 s80, 12
	s_cbranch_scc1 .Lipf_hgb
	s_sub_u32 s0, s80, 14
	s_cmp_lt_u32 s0, 7
	s_cbranch_scc1 .Lipf_hg
	s_cmp_eq_u32 s80, 11
	s_cbranch_scc1 .Lipg_11
	s_cmp_eq_u32 s80, 13
	s_cbranch_scc1 .Lipg_13
	s_cmp_eq_u32 s80, 21
	s_cbranch_scc1 .Lipg_21
	s_cmp_eq_u32 s80, 5
	s_cbranch_scc1 .Lipg_5
	s_cmp_eq_u32 s80, 2
	s_cbranch_scc1 .Lipk
	s_branch .Lipf_slow

.Lipg_21:
	s_mov_b32 s44, 0x12380000
	s_mov_b32 s45, 0xd50
	s_mov_b32 s52, 0x1000
	s_mov_b32 s54, 0x0
	s_mov_b32 s60, 0x0
	s_mov_b32 s62, 0x0
	s_mov_b32 s63, 0x1550
	s_mov_b32 s56, 0x7fffffff
	s_mov_b32 s53, 0x0
	s_mov_b32 s57, 0x1550
	s_mov_b32 s82, 0x0
	s_branch .Lipg_common
.Lipg_5:
	s_cmpk_gt_i32 s81, 0x7f
	s_cbranch_scc1 .Lipf_slow
	s_and_b32 s0, s81, 15
	s_cmp_eq_u32 s0, 15
	s_cbranch_scc1 .Lipf_slow
	s_mov_b32 s44, 0x22982200
	s_mov_b32 s45, 0x500
	s_mov_b32 s52, 0x80
	s_mov_b32 s54, 0xa180000
	s_mov_b32 s60, 0x548
	s_mov_b32 s62, 0xc00
	s_mov_b32 s63, 0x540
	s_mov_b32 s56, 0x548
	s_mov_b32 s53, 0x7fffffff
	s_mov_b32 s57, 0x7fffffff
	s_mov_b32 s82, 0x2

.Lipg_noab:
	s_cmp_eq_u32 s82, 2
	s_cbranch_scc0 .Lipg_nokx
	s_sub_u32 s0, s88, s83
	s_cmp_lt_u32 s0, 64
	s_cbranch_scc0 .Lipg_wi
	s_lshl_b64 s[58:59], s[64:65], 2
	s_add_u32 s58, s58, s16
	s_addc_u32 s59, s59, s17
	v_lshlrev_b32_e32 v192, 8, v176
	v_lshl_add_u32 v196, v135, 2, v192
	v_mov_b32_e32 v197, 0
	v_lshl_add_u64 v[196:197], v[196:197], 0, s[58:59]
	s_mov_b32 s42, 0x0
	v_lshl_add_u64 v[198:199], v[196:197], 0, s[42:43]
	global_store_dwordx4 v[198:199], v[130:133], off offset:0
	global_store_dwordx4 v[198:199], v[94:97], off offset:64
	s_mov_b32 s42, 0x1000
	v_lshl_add_u64 v[198:199], v[196:197], 0, s[42:43]
	global_store_dwordx4 v[198:199], v[126:129], off offset:0
	global_store_dwordx4 v[198:199], v[90:93], off offset:64
	s_mov_b32 s42, 0x2000
	v_lshl_add_u64 v[198:199], v[196:197], 0, s[42:43]
	global_store_dwordx4 v[198:199], v[122:125], off offset:0
	global_store_dwordx4 v[198:199], v[86:89], off offset:64
	s_mov_b32 s42, 0x3000
	v_lshl_add_u64 v[198:199], v[196:197], 0, s[42:43]
	global_store_dwordx4 v[198:199], v[118:121], off offset:0
	global_store_dwordx4 v[198:199], v[82:85], off offset:64
	s_mov_b32 s42, 0x8000
	v_lshl_add_u64 v[198:199], v[196:197], 0, s[42:43]
	global_store_dwordx4 v[198:199], v[114:117], off offset:0
	global_store_dwordx4 v[198:199], v[78:81], off offset:64
	s_mov_b32 s42, 0x9000
	v_lshl_add_u64 v[198:199], v[196:197], 0, s[42:43]
	global_store_dwordx4 v[198:199], v[106:109], off offset:0
	global_store_dwordx4 v[198:199], v[74:77], off offset:64
	s_mov_b32 s42, 0xa000
	v_lshl_add_u64 v[198:199], v[196:197], 0, s[42:43]
	global_store_dwordx4 v[198:199], v[102:105], off offset:0
	global_store_dwordx4 v[198:199], v[70:73], off offset:64
	s_mov_b32 s42, 0xb000
	v_lshl_add_u64 v[198:199], v[196:197], 0, s[42:43]
	global_store_dwordx4 v[198:199], v[98:101], off offset:0
	global_store_dwordx4 v[198:199], v[66:69], off offset:64
	s_nop 1
	s_branch .Lipg_nokx
.Lipg_wi:
	s_cmp_eq_u32 s0, 64
	s_cbranch_scc0 .Lipg_nokx
	s_add_u32 s58, s12, 0x23e96200
	s_addc_u32 s59, s13, 0
	v_lshrrev_b32_e32 v192, 4, v219
	v_lshlrev_b32_e32 v192, 4, v192
	v_lshl_add_u32 v196, v176, 5, v192
	v_mov_b32_e32 v197, 0
	v_lshl_add_u64 v[196:197], v[196:197], 0, s[58:59]
	s_movk_i32 s42, 0x1000
	v_lshl_add_u64 v[198:199], v[196:197], 0, s[42:43]
	s_mov_b32 exec_lo, -1
	s_mov_b32 exec_hi, 0
	v_mul_f32_e32 v130, 0x3d3504f3, v130
	v_mul_f32_e32 v131, 0x3d3504f3, v131
	v_mul_f32_e32 v132, 0x3d3504f3, v132
	v_mul_f32_e32 v133, 0x3d3504f3, v133
	v_mul_f32_e32 v126, 0x3d3504f3, v126
	v_mul_f32_e32 v127, 0x3d3504f3, v127
	v_mul_f32_e32 v128, 0x3d3504f3, v128
	v_mul_f32_e32 v129, 0x3d3504f3, v129
	v_mul_f32_e32 v122, 0x3d3504f3, v122
	v_mul_f32_e32 v123, 0x3d3504f3, v123
	v_mul_f32_e32 v124, 0x3d3504f3, v124
	v_mul_f32_e32 v125, 0x3d3504f3, v125
	v_mul_f32_e32 v118, 0x3d3504f3, v118
	v_mul_f32_e32 v119, 0x3d3504f3, v119
	v_mul_f32_e32 v120, 0x3d3504f3, v120
	v_mul_f32_e32 v121, 0x3d3504f3, v121
	v_mul_f32_e32 v114, 0x3d3504f3, v114
	v_mul_f32_e32 v115, 0x3d3504f3, v115
	v_mul_f32_e32 v116, 0x3d3504f3, v116
	v_mul_f32_e32 v117, 0x3d3504f3, v117
	v_mul_f32_e32 v106, 0x3d3504f3, v106
	v_mul_f32_e32 v107, 0x3d3504f3, v107
	v_mul_f32_e32 v108, 0x3d3504f3, v108
	v_mul_f32_e32 v109, 0x3d3504f3, v109
	v_mul_f32_e32 v102, 0x3d3504f3, v102
	v_mul_f32_e32 v103, 0x3d3504f3, v103
	v_mul_f32_e32 v104, 0x3d3504f3, v104
	v_mul_f32_e32 v105, 0x3d3504f3, v105
	v_mul_f32_e32 v98, 0x3d3504f3, v98
	v_mul_f32_e32 v99, 0x3d3504f3, v99
	v_mul_f32_e32 v100, 0x3d3504f3, v100
	v_mul_f32_e32 v101, 0x3d3504f3, v101
	global_store_dwordx4 v[196:197], v[130:133], off offset:0
	global_store_dwordx4 v[196:197], v[126:129], off offset:512
	global_store_dwordx4 v[196:197], v[122:125], off offset:1024
	global_store_dwordx4 v[196:197], v[118:121], off offset:1536
	global_store_dwordx4 v[198:199], v[114:117], off offset:0
	global_store_dwordx4 v[198:199], v[106:109], off offset:512
	global_store_dwordx4 v[198:199], v[102:105], off offset:1024
	global_store_dwordx4 v[198:199], v[98:101], off offset:1536
	s_mov_b64 exec, -1
	s_nop 1

.Lipk:
	s_lshl_b32 s60, s81, 8
	s_mov_b32 s43, 0
	s_cmpk_gt_i32 s81, 0x7f
	s_cselect_b32 s53, 1, 0
	s_cselect_b32 s0, s74, s72
	s_cselect_b32 s57, s75, s73
	s_mov_b32 s56, s0
	s_cselect_b32 s0, s70, s68
	s_cselect_b32 s59, s71, s69
	s_mov_b32 s58, s0
	s_lshl_b64 s[56:57], s[56:57], 2
	s_lshl_b64 s[58:59], s[58:59], 2
	s_add_u32 s56, s56, s16
	s_addc_u32 s57, s57, s17
	s_add_u32 s58, s58, s16
	s_addc_u32 s59, s59, s17
	v_add_u32_e32 v176, s60, v150
	s_lshl_b32 s0, s53, 15
	v_subrev_u32_e32 v178, s0, v176
	v_lshlrev_b32_e32 v178, 9, v178
	v_lshl_add_u32 v178, v135, 2, v178
	v_mov_b32_e32 v179, 0
	v_lshl_add_u64 v[152:153], v[178:179], 0, s[56:57]
	v_lshl_add_u64 v[154:155], v[178:179], 0, s[58:59]
	v_lshrrev_b32_e32 v178, 4, v219
	v_and_b32_e32 v179, 1, v178
	v_lshrrev_b32_e32 v178, 1, v178
	v_lshl_add_u32 v178, v179, 1, v178
	v_lshlrev_b32_e32 v178, 4, v178
	v_bfe_u32 v179, v211, 6, 2
	v_lshl_add_u32 v178, v179, 6, v178
	v_lshl_add_u32 v178, v176, 8, v178
	v_mov_b32_e32 v179, 0
	s_add_u32 s62, s12, 0x21982200
	s_addc_u32 s63, s13, 0
	v_lshl_add_u64 v[156:157], v[178:179], 0, s[62:63]
	s_add_u32 s62, s12, 0x22182200
	s_addc_u32 s63, s13, 0
	v_lshl_add_u64 v[158:159], v[178:179], 0, s[62:63]
	s_nop 7
	s_nop 7
	s_mov_b32 s42, 0x0
	v_lshl_add_u64 v[160:161], v[152:153], 0, s[42:43]
	v_lshl_add_u64 v[162:163], v[154:155], 0, s[42:43]
	global_store_dwordx4 v[160:161], v[130:133], off offset:0
	global_store_dwordx4 v[160:161], v[94:97], off offset:64
	global_store_dwordx4 v[162:163], v[62:65], off offset:0
	global_store_dwordx4 v[162:163], v[30:33], off offset:64
	s_cmp_eq_u32 s53, 0
	s_cbranch_scc0 .Lipk_s0
	s_mov_b32 s42, 0x0
	v_lshl_add_u64 v[164:165], v[156:157], 0, s[42:43]
	v_lshl_add_u64 v[166:167], v[158:159], 0, s[42:43]
	v_cvt_pk_bf16_f32 v130, v130, v131
	v_cvt_pk_bf16_f32 v131, v132, v133
	v_cvt_pk_bf16_f32 v132, v94, v95
	v_cvt_pk_bf16_f32 v133, v96, v97
	v_cvt_pk_bf16_f32 v62, v62, v63
	v_cvt_pk_bf16_f32 v63, v64, v65
	v_cvt_pk_bf16_f32 v64, v30, v31
	v_cvt_pk_bf16_f32 v65, v32, v33
	v_permlane16_swap_b32_e32 v130, v132
	v_permlane16_swap_b32_e32 v131, v133
	v_permlane16_swap_b32_e32 v62, v64
	v_permlane16_swap_b32_e32 v63, v65
	global_store_dwordx4 v[164:165], v[130:133], off
	global_store_dwordx4 v[166:167], v[62:65], off
.Lipk_s0:
	s_mov_b32 s42, 0x2000
	v_lshl_add_u64 v[160:161], v[152:153], 0, s[42:43]
	v_lshl_add_u64 v[162:163], v[154:155], 0, s[42:43]
	global_store_dwordx4 v[160:161], v[126:129], off offset:0
	global_store_dwordx4 v[160:161], v[90:93], off offset:64
	global_store_dwordx4 v[162:163], v[58:61], off offset:0
	global_store_dwordx4 v[162:163], v[26:29], off offset:64
	s_cmp_eq_u32 s53, 0
	s_cbranch_scc0 .Lipk_s1
	s_mov_b32 s42, 0x1000
	v_lshl_add_u64 v[164:165], v[156:157], 0, s[42:43]
	v_lshl_add_u64 v[166:167], v[158:159], 0, s[42:43]
	v_cvt_pk_bf16_f32 v126, v126, v127
	v_cvt_pk_bf16_f32 v127, v128, v129
	v_cvt_pk_bf16_f32 v128, v90, v91
	v_cvt_pk_bf16_f32 v129, v92, v93
	v_cvt_pk_bf16_f32 v58, v58, v59
	v_cvt_pk_bf16_f32 v59, v60, v61
	v_cvt_pk_bf16_f32 v60, v26, v27
	v_cvt_pk_bf16_f32 v61, v28, v29
	v_permlane16_swap_b32_e32 v126, v128
	v_permlane16_swap_b32_e32 v127, v129
	v_permlane16_swap_b32_e32 v58, v60
	v_permlane16_swap_b32_e32 v59, v61
	global_store_dwordx4 v[164:165], v[126:129], off
	global_store_dwordx4 v[166:167], v[58:61], off
.Lipk_s1:
	s_mov_b32 s42, 0x4000
	v_lshl_add_u64 v[160:161], v[152:153], 0, s[42:43]
	v_lshl_add_u64 v[162:163], v[154:155], 0, s[42:43]
	global_store_dwordx4 v[160:161], v[122:125], off offset:0
	global_store_dwordx4 v[160:161], v[86:89], off offset:64
	global_store_dwordx4 v[162:163], v[54:57], off offset:0
	global_store_dwordx4 v[162:163], v[22:25], off offset:64
	s_cmp_eq_u32 s53, 0
	s_cbranch_scc0 .Lipk_s2
	s_mov_b32 s42, 0x2000
	v_lshl_add_u64 v[164:165], v[156:157], 0, s[42:43]
	v_lshl_add_u64 v[166:167], v[158:159], 0, s[42:43]
	v_cvt_pk_bf16_f32 v122, v122, v123
	v_cvt_pk_bf16_f32 v123, v124, v125
	v_cvt_pk_bf16_f32 v124, v86, v87
	v_cvt_pk_bf16_f32 v125, v88, v89
	v_cvt_pk_bf16_f32 v54, v54, v55
	v_cvt_pk_bf16_f32 v55, v56, v57
	v_cvt_pk_bf16_f32 v56, v22, v23
	v_cvt_pk_bf16_f32 v57, v24, v25
	v_permlane16_swap_b32_e32 v122, v124
	v_permlane16_swap_b32_e32 v123, v125
	v_permlane16_swap_b32_e32 v54, v56
	v_permlane16_swap_b32_e32 v55, v57
	global_store_dwordx4 v[164:165], v[122:125], off
	global_store_dwordx4 v[166:167], v[54:57], off
.Lipk_s2:
	s_mov_b32 s42, 0x6000
	v_lshl_add_u64 v[160:161], v[152:153], 0, s[42:43]
	v_lshl_add_u64 v[162:163], v[154:155], 0, s[42:43]
	global_store_dwordx4 v[160:161], v[118:121], off offset:0
	global_store_dwordx4 v[160:161], v[82:85], off offset:64
	global_store_dwordx4 v[162:163], v[50:53], off offset:0
	global_store_dwordx4 v[162:163], v[18:21], off offset:64
	s_cmp_eq_u32 s53, 0
	s_cbranch_scc0 .Lipk_s3
	s_mov_b32 s42, 0x3000
	v_lshl_add_u64 v[164:165], v[156:157], 0, s[42:43]
	v_lshl_add_u64 v[166:167], v[158:159], 0, s[42:43]
	v_cvt_pk_bf16_f32 v118, v118, v119
	v_cvt_pk_bf16_f32 v119, v120, v121
	v_cvt_pk_bf16_f32 v120, v82, v83
	v_cvt_pk_bf16_f32 v121, v84, v85
	v_cvt_pk_bf16_f32 v50, v50, v51
	v_cvt_pk_bf16_f32 v51, v52, v53
	v_cvt_pk_bf16_f32 v52, v18, v19
	v_cvt_pk_bf16_f32 v53, v20, v21
	v_permlane16_swap_b32_e32 v118, v120
	v_permlane16_swap_b32_e32 v119, v121
	v_permlane16_swap_b32_e32 v50, v52
	v_permlane16_swap_b32_e32 v51, v53
	global_store_dwordx4 v[164:165], v[118:121], off
	global_store_dwordx4 v[166:167], v[50:53], off
.Lipk_s3:
	s_mov_b32 s42, 0x10000
	v_lshl_add_u64 v[160:161], v[152:153], 0, s[42:43]
	v_lshl_add_u64 v[162:163], v[154:155], 0, s[42:43]
	global_store_dwordx4 v[160:161], v[114:117], off offset:0
	global_store_dwordx4 v[160:161], v[78:81], off offset:64
	global_store_dwordx4 v[162:163], v[46:49], off offset:0
	global_store_dwordx4 v[162:163], v[14:17], off offset:64
	s_cmp_eq_u32 s53, 0
	s_cbranch_scc0 .Lipk_s4
	s_mov_b32 s42, 0x8000
	v_lshl_add_u64 v[164:165], v[156:157], 0, s[42:43]
	v_lshl_add_u64 v[166:167], v[158:159], 0, s[42:43]
	v_cvt_pk_bf16_f32 v114, v114, v115
	v_cvt_pk_bf16_f32 v115, v116, v117
	v_cvt_pk_bf16_f32 v116, v78, v79
	v_cvt_pk_bf16_f32 v117, v80, v81
	v_cvt_pk_bf16_f32 v46, v46, v47
	v_cvt_pk_bf16_f32 v47, v48, v49
	v_cvt_pk_bf16_f32 v48, v14, v15
	v_cvt_pk_bf16_f32 v49, v16, v17
	v_permlane16_swap_b32_e32 v114, v116
	v_permlane16_swap_b32_e32 v115, v117
	v_permlane16_swap_b32_e32 v46, v48
	v_permlane16_swap_b32_e32 v47, v49
	global_store_dwordx4 v[164:165], v[114:117], off
	global_store_dwordx4 v[166:167], v[46:49], off
.Lipk_s4:
	s_mov_b32 s42, 0x12000
	v_lshl_add_u64 v[160:161], v[152:153], 0, s[42:43]
	v_lshl_add_u64 v[162:163], v[154:155], 0, s[42:43]
	global_store_dwordx4 v[160:161], v[106:109], off offset:0
	global_store_dwordx4 v[160:161], v[74:77], off offset:64
	global_store_dwordx4 v[162:163], v[42:45], off offset:0
	global_store_dwordx4 v[162:163], v[10:13], off offset:64
	s_cmp_eq_u32 s53, 0
	s_cbranch_scc0 .Lipk_s5
	s_mov_b32 s42, 0x9000
	v_lshl_add_u64 v[164:165], v[156:157], 0, s[42:43]
	v_lshl_add_u64 v[166:167], v[158:159], 0, s[42:43]
	v_cvt_pk_bf16_f32 v106, v106, v107
	v_cvt_pk_bf16_f32 v107, v108, v109
	v_cvt_pk_bf16_f32 v108, v74, v75
	v_cvt_pk_bf16_f32 v109, v76, v77
	v_cvt_pk_bf16_f32 v42, v42, v43
	v_cvt_pk_bf16_f32 v43, v44, v45
	v_cvt_pk_bf16_f32 v44, v10, v11
	v_cvt_pk_bf16_f32 v45, v12, v13
	v_permlane16_swap_b32_e32 v106, v108
	v_permlane16_swap_b32_e32 v107, v109
	v_permlane16_swap_b32_e32 v42, v44
	v_permlane16_swap_b32_e32 v43, v45
	global_store_dwordx4 v[164:165], v[106:109], off
	global_store_dwordx4 v[166:167], v[42:45], off
.Lipk_s5:
	s_mov_b32 s42, 0x14000
	v_lshl_add_u64 v[160:161], v[152:153], 0, s[42:43]
	v_lshl_add_u64 v[162:163], v[154:155], 0, s[42:43]
	global_store_dwordx4 v[160:161], v[102:105], off offset:0
	global_store_dwordx4 v[160:161], v[70:73], off offset:64
	global_store_dwordx4 v[162:163], v[38:41], off offset:0
	global_store_dwordx4 v[162:163], v[6:9], off offset:64
	s_cmp_eq_u32 s53, 0
	s_cbranch_scc0 .Lipk_s6
	s_mov_b32 s42, 0xa000
	v_lshl_add_u64 v[164:165], v[156:157], 0, s[42:43]
	v_lshl_add_u64 v[166:167], v[158:159], 0, s[42:43]
	v_cvt_pk_bf16_f32 v102, v102, v103
	v_cvt_pk_bf16_f32 v103, v104, v105
	v_cvt_pk_bf16_f32 v104, v70, v71
	v_cvt_pk_bf16_f32 v105, v72, v73
	v_cvt_pk_bf16_f32 v38, v38, v39
	v_cvt_pk_bf16_f32 v39, v40, v41
	v_cvt_pk_bf16_f32 v40, v6, v7
	v_cvt_pk_bf16_f32 v41, v8, v9
	v_permlane16_swap_b32_e32 v102, v104
	v_permlane16_swap_b32_e32 v103, v105
	v_permlane16_swap_b32_e32 v38, v40
	v_permlane16_swap_b32_e32 v39, v41
	global_store_dwordx4 v[164:165], v[102:105], off
	global_store_dwordx4 v[166:167], v[38:41], off
.Lipk_s6:
	s_mov_b32 s42, 0x16000
	v_lshl_add_u64 v[160:161], v[152:153], 0, s[42:43]
	v_lshl_add_u64 v[162:163], v[154:155], 0, s[42:43]
	global_store_dwordx4 v[160:161], v[98:101], off offset:0
	global_store_dwordx4 v[160:161], v[66:69], off offset:64
	global_store_dwordx4 v[162:163], v[34:37], off offset:0
	global_store_dwordx4 v[162:163], v[2:5], off offset:64
	s_cmp_eq_u32 s53, 0
	s_cbranch_scc0 .Lipk_s7
	s_mov_b32 s42, 0xb000
	v_lshl_add_u64 v[164:165], v[156:157], 0, s[42:43]
	v_lshl_add_u64 v[166:167], v[158:159], 0, s[42:43]
	v_cvt_pk_bf16_f32 v98, v98, v99
	v_cvt_pk_bf16_f32 v99, v100, v101
	v_cvt_pk_bf16_f32 v100, v66, v67
	v_cvt_pk_bf16_f32 v101, v68, v69
	v_cvt_pk_bf16_f32 v34, v34, v35
	v_cvt_pk_bf16_f32 v35, v36, v37
	v_cvt_pk_bf16_f32 v36, v2, v3
	v_cvt_pk_bf16_f32 v37, v4, v5
	v_permlane16_swap_b32_e32 v98, v100
	v_permlane16_swap_b32_e32 v99, v101
	v_permlane16_swap_b32_e32 v34, v36
	v_permlane16_swap_b32_e32 v35, v37
	global_store_dwordx4 v[164:165], v[98:101], off
	global_store_dwordx4 v[166:167], v[34:37], off
.Lipk_s7:
	s_branch .LBB0_986
.Lipf_slow:
	s_cmpk_gt_i32 s81, 0x7f
	s_cselect_b64 s[40:41], -1, 0
	s_cmpk_lt_i32 s81, 0x80
	s_cselect_b64 s[0:1], -1, 0
	s_and_b64 s[8:9], s[0:1], exec
	s_cselect_b32 s82, 0, 0x8000
	s_lshl_b32 s3, s82, 5
	v_or_b32_e32 v136, s42, v135
	s_add_u32 s44, s12, s3
	v_add_u32_e32 v151, s2, v150
	s_movk_i32 s2, 0x1550
	s_addc_u32 s45, s13, 0
	v_cmp_gt_i32_e32 vcc, s2, v136
	s_and_saveexec_b64 s[46:47], vcc
	s_cbranch_execz .LBB0_1155
	s_movk_i32 s2, 0x1ff
	v_cmp_lt_i32_e32 vcc, s2, v136
	s_and_saveexec_b64 s[8:9], vcc
	s_xor_b64 s[8:9], exec, s[8:9]
	s_cbranch_execz .LBB0_1039
	s_cmpk_gt_u32 s42, 0x27f
	s_mov_b64 s[52:53], -1
	s_cbranch_scc0 .LBB0_1037
	s_cmpk_gt_u32 s42, 0x2ff
	s_cbranch_scc0 .LBB0_1034
	s_cmpk_gt_u32 s42, 0x4ff
	s_cbranch_scc0 .LBB0_1031
	s_movk_i32 s2, 0x53f
	v_cmp_lt_u32_e32 vcc, s2, v136
	s_and_saveexec_b64 s[52:53], vcc
	s_xor_b64 s[52:53], exec, s[52:53]
	s_cbranch_execz .LBB0_1024
	s_movk_i32 s2, 0x547
	v_cmp_lt_u32_e32 vcc, s2, v136
	s_and_saveexec_b64 s[50:51], vcc
	s_xor_b64 s[50:51], exec, s[50:51]
	s_cbranch_execz .LBB0_1021
	s_movk_i32 s2, 0xb47
	v_cmp_lt_u32_e32 vcc, s2, v136
	s_and_saveexec_b64 s[48:49], vcc
	s_xor_b64 s[48:49], exec, s[48:49]
	s_cbranch_execz .LBB0_1018
	s_movk_i32 s2, 0xb4f
	v_cmp_lt_u32_e32 vcc, s2, v136
	s_and_saveexec_b64 s[54:55], vcc
	s_xor_b64 s[54:55], exec, s[54:55]
	s_cbranch_execz .LBB0_1015
	s_movk_i32 s2, 0xd4f
	v_cmp_lt_u32_e32 vcc, s2, v136
	s_and_saveexec_b64 s[2:3], vcc
	s_xor_b64 s[2:3], exec, s[2:3]
	s_cbranch_execz .LBB0_1012
	v_add_u32_e32 v0, 0xfffff2b0, v136
	v_lshl_add_u64 v[110:111], v[0:1], 2, s[10:11]
	global_load_dwordx4 v[110:113], v[110:111], off
	s_waitcnt vmcnt(0)
	v_lshl_add_u64 v[138:139], v[0:1], 1, s[18:19]
